# sample-row workgroups moved to the upper half of the grid (overlaps the per-row scale reduction done by workgroups 0-15)
# baseline (speedup 1.0000x reference)
; #define x_sample ((const float*)KPTR(1))
; __global__ void __launch_bounds__(NTHR, 2) fwd_kernel(Args a) {
;     ...
;               for (int m = MP + gw; m < MREAL; m += NGW) {
;                   if (rp_ == 0) sample_assemble(l == 0 ? x_sample + (size_t)(m - MP) * DM : XR + (size_t)m * DM, XSP, 8, m - MP, XR + (size_t)m * DM, lane);
;                   row_bf16_ss(XR + (size_t)m * DM, XN + (size_t)m * DM, SSB + (size_t)(2 * l + 1) * MPAD + m, lane); } }
.LBB0_714:
	s_or_b64 exec, exec, s[4:5]
	s_ashr_i32 s6, s6, 6
	v_readlane_b32 s0, v245, 26
	s_sub_i32 s4, s0, 0x2000
	s_lshr_b32 s4, s4, 3
	s_lshr_b32 s5, s96, 4
	s_add_i32 s4, s4, s5
	s_lshr_b32 s5, s96, 3
	s_cmp_ge_u32 s4, s5
	s_cselect_b32 s5, s5, 0
	s_sub_i32 s4, s4, s5
	s_lshr_b32 s5, s96, 3
	s_mul_i32 s5, s5, s6
	s_add_i32 s4, s4, s5
	s_addk_i32 s4, 0x2000
	s_cmpk_gt_i32 s4, 0x207f
	s_cbranch_scc1 .LBB0_723
	s_load_dwordx2 s[8:9], s[2:3], 0x98
	v_and_b32_e32 v0, 63, v6
	v_lshlrev_b32_e32 v168, 4, v0
	s_mov_b64 s[22:23], 0xe700000
	v_and_b32_e32 v1, 64, v211
	s_waitcnt lgkmcnt(0)
	v_lshl_add_u64 v[2:3], s[8:9], 0, v[168:169]
	v_lshl_add_u64 v[32:33], v[2:3], 0, s[22:23]
	s_mov_b64 s[22:23], 0x216e4000
	v_lshl_add_u64 v[34:35], v[2:3], 0, s[22:23]
	v_add_u32_e32 v1, 64, v1
	v_xor_b32_e32 v2, 1, v211
	v_cmp_lt_i32_e32 vcc, v2, v1
	v_lshlrev_b32_e32 v168, 3, v0
	v_readlane_b32 s0, v244, 34
	v_cndmask_b32_e32 v2, v211, v2, vcc
	v_lshlrev_b32_e32 v38, 2, v2
	v_xor_b32_e32 v2, 2, v211
	v_cmp_lt_i32_e32 vcc, v2, v1
	s_mov_b64 s[22:23], 0xc600000
	v_readlane_b32 s1, v244, 35
	v_cndmask_b32_e32 v2, v211, v2, vcc
	v_lshlrev_b32_e32 v39, 2, v2
	v_xor_b32_e32 v2, 4, v211
	v_cmp_lt_i32_e32 vcc, v2, v1
	v_cmp_eq_u32_e64 s[40:41], 0, v0
	s_nop 0
	v_cndmask_b32_e32 v2, v211, v2, vcc
	v_lshlrev_b32_e32 v40, 2, v2
	v_xor_b32_e32 v2, 8, v211
	v_cmp_lt_i32_e32 vcc, v2, v1
	s_nop 1
	v_cndmask_b32_e32 v2, v211, v2, vcc
	v_lshlrev_b32_e32 v41, 2, v2
	v_xor_b32_e32 v2, 16, v211
	v_cmp_lt_i32_e32 vcc, v2, v1
	s_nop 1
	v_cndmask_b32_e32 v2, v211, v2, vcc
	v_lshlrev_b32_e32 v42, 2, v2
	v_xor_b32_e32 v2, 32, v211
	v_cmp_lt_i32_e32 vcc, v2, v1
	s_nop 1
	v_cndmask_b32_e32 v1, v211, v2, vcc
	v_lshl_add_u64 v[2:3], s[8:9], 0, v[168:169]
	v_lshl_add_u64 v[36:37], v[2:3], 0, s[22:23]
	s_lshl_b64 s[22:23], s[0:1], 2
	s_add_u32 s5, s8, s22
	s_addc_u32 s7, s9, s23
	s_add_u32 s10, s5, 0x221f0400
	v_readlane_b32 s0, v246, 4
	s_addc_u32 s34, s7, 0
	s_ashr_i32 s5, s4, 31
	s_add_i32 s24, s4, 0xffffe000
	v_readlane_b32 s0, v244, 30
	v_lshlrev_b32_e32 v43, 2, v1
	s_lshl_b64 s[22:23], s[4:5], 13
	v_readlane_b32 s1, v244, 31
	v_lshlrev_b32_e32 v168, 4, v0
	s_branch .LBB0_717

; __global__ void __launch_bounds__(NTHR, 2) fwd_kernel(Args a) {
;     ...
;               for (int m = MP + gw; m < MREAL; m += NGW) { sample_assemble(XR + (size_t)m * DM, XSP, 11, m - MP, XR + (size_t)m * DM, lane);
;                   row_bf16_ss(XR + (size_t)m * DM, XN + (size_t)m * DM, SSB + (size_t)2 * MPAD + m, lane); }
.LBB0_1016:
	s_or_b64 exec, exec, s[0:1]
	s_ashr_i32 s4, s6, 6
	v_readlane_b32 s0, v245, 26
	s_sub_i32 s0, s0, 0x2000
	s_lshr_b32 s0, s0, 3
	s_lshr_b32 s5, s96, 4
	s_add_i32 s0, s0, s5
	s_lshr_b32 s5, s96, 3
	s_cmp_ge_u32 s0, s5
	s_cselect_b32 s5, s5, 0
	s_sub_i32 s0, s0, s5
	s_lshr_b32 s5, s96, 3
	s_mul_i32 s5, s5, s4
	s_add_i32 s0, s0, s5
	s_addk_i32 s0, 0x2000
	s_cmpk_gt_i32 s0, 0x207f
	s_cbranch_scc1 .LBB0_1021
	v_and_b32_e32 v1, 64, v211
	v_add_u32_e32 v1, 64, v1
	v_xor_b32_e32 v2, 1, v211
	v_cmp_lt_i32_e32 vcc, v2, v1
	s_ashr_i32 s1, s0, 31
	s_lshl_b64 s[6:7], s[0:1], 2
	v_cndmask_b32_e32 v2, v211, v2, vcc
	v_lshlrev_b32_e32 v62, 2, v2
	v_xor_b32_e32 v2, 2, v211
	v_cmp_lt_i32_e32 vcc, v2, v1
	s_add_u32 s6, s6, 0x221f8800
	v_and_b32_e32 v0, 63, v6
	v_cndmask_b32_e32 v2, v211, v2, vcc
	v_lshlrev_b32_e32 v63, 2, v2
	v_xor_b32_e32 v2, 4, v211
	v_cmp_lt_i32_e32 vcc, v2, v1
	s_addc_u32 s7, s7, 0
	s_lshl_b64 s[8:9], s[0:1], 12
	v_cndmask_b32_e32 v2, v211, v2, vcc
	v_lshlrev_b32_e32 v64, 2, v2
	v_xor_b32_e32 v2, 8, v211
	v_cmp_lt_i32_e32 vcc, v2, v1
	s_load_dwordx2 s[2:3], s[2:3], 0x98
	v_lshl_or_b32 v32, v0, 3, s8
	v_cndmask_b32_e32 v2, v211, v2, vcc
	v_lshlrev_b32_e32 v65, 2, v2
	v_xor_b32_e32 v2, 16, v211
	v_cmp_lt_i32_e32 vcc, v2, v1
	v_mov_b32_e32 v33, s9
	s_lshl_b64 s[8:9], s[0:1], 13
	v_cndmask_b32_e32 v2, v211, v2, vcc
	v_readlane_b32 s1, v246, 4
	v_lshlrev_b32_e32 v66, 2, v2
	v_xor_b32_e32 v2, 32, v211
	s_add_i32 s4, s0, 0xffffe000
	v_cmp_lt_i32_e32 vcc, v2, v1
	s_ashr_i32 s5, s4, 31
	v_cmp_eq_u32_e64 s[40:41], 0, v0
	v_cndmask_b32_e32 v1, v211, v2, vcc
	v_lshlrev_b32_e32 v0, 4, v0
	s_lshl_b64 s[4:5], s[4:5], 13
	v_lshlrev_b32_e32 v67, 2, v1
	v_or_b32_e32 v34, s8, v0
	v_mov_b32_e32 v35, s9
	v_or_b32_e32 v36, s4, v0
	v_mov_b32_e32 v37, s5
	s_branch .LBB0_1019
